# shortens the scalar address chain of the LDS-DMA loads in GEMM phases 3 and 4 (no in-place advance and undo of the A base pointer)
# baseline (speedup 1.0000x reference)
; #define PG8_STAGE(bufoff, gbase, voff) do { _Pragma("unroll") for (int _i = 0; _i < 2; ++_i) \
;         __builtin_amdgcn_global_load_lds((const unsigned*)((const char*)(gbase) + (voff)[_i]), (LAS unsigned*)(lds + (bufoff) + ldsw + _i * 8192), 16, 0, 0); } while (0)
; #define PG8_LDA(dst, b, h) do { _Pragma("unroll") for (int m = 0; m < 4; ++m) _Pragma("unroll") for (int k = 0; k < 2; ++k) dst[m][k] = *(const LAS bf16x8*)(lds + PG8_SA(b, h) + aoff + m * 2048 + k * 1024); } while (0)
; #define PG8_LDB(dst, b, h) do { _Pragma("unroll") for (int n = 0; n < 2; ++n) _Pragma("unroll") for (int k = 0; k < 2; ++k) dst[n][k] = *(const LAS bf16x8*)(lds + PG8_SB(b, h) + boff + n * 2048 + k * 1024); } while (0)
; #define PG8_MMA(ai, bj, At, Bt) do { __builtin_amdgcn_s_setprio(1); _Pragma("unroll") for (int m = 0; m < 4; ++m) _Pragma("unroll") for (int n = 0; n < 2; ++n) _Pragma("unroll") for (int k = 0; k < 2; ++k) \
;         acc[ai][bj][m][n] = __builtin_amdgcn_mfma_f32_16x16x32_bf16(Bt[n][k], At[m][k], acc[ai][bj][m][n], 0, 0, 0); __builtin_amdgcn_s_setprio(0); } while (0)
; #define PG8_WAIT_V(n) asm volatile("s_waitcnt vmcnt(" #n ")" ::: "memory")
; #define PG8_WAIT_L(n) asm volatile("s_waitcnt lgkmcnt(" #n ")" ::: "memory")
; #define PG8_BAR __builtin_amdgcn_s_barrier()
; #define PG8_SCHED __builtin_amdgcn_sched_barrier(0)
; __device__ __forceinline__ void gemm_phase(LAS unsigned char* lds, const Gemm g, const StaticOrder& S, const Epi& E) {
;     ...
;             PG8_LDB(B0, 0, 0); PG8_LDB(B1, 0, 1); PG8_SCHED; PG8_LDA(At, 0, 0); PG8_STAGE(PG8_SA(1, 1), a1 + hstepA, voffA);
;             PG8_WAIT_V(8); PG8_WAIT_L(0); PG8_BAR; PG8_MMA(0, 0, At, B0); PG8_MMA(0, 1, At, B1); PG8_BAR; PG8_SCHED;
;             PG8_LDA(At, 0, 1); PG8_STAGE(PG8_SB(0, 0), b2, voffB); PG8_STAGE(PG8_SB(0, 1), b2 + hstepB, voffB); PG8_STAGE(PG8_SA(0, 0), a2, voffA);
;             PG8_WAIT_V(8); PG8_WAIT_L(0); PG8_BAR; PG8_MMA(1, 0, At, B0); PG8_MMA(1, 1, At, B1); PG8_BAR; PG8_SCHED;
.LBB0_177:
	s_waitcnt lgkmcnt(0)
	ds_read_b128 v[130:133], v226
	ds_read_b128 v[134:137], v226 offset:1024
	ds_read_b128 v[138:141], v226 offset:2048
	ds_read_b128 v[142:145], v226 offset:3072
	ds_read_b128 v[146:149], v227
	ds_read_b128 v[150:153], v227 offset:1024
	ds_read_b128 v[154:157], v227 offset:2048
	ds_read_b128 v[182:185], v227 offset:3072
	s_add_i32 s27, s17, 2
	s_add_u32 s2, s0, 0x80
	s_addc_u32 s3, s1, 0
	s_cmp_eq_u32 s85, s17
	s_cselect_b32 s3, s7, s3
	s_cselect_b32 s2, s6, s2
	s_cselect_b32 s41, s95, s16
	s_cselect_b32 s40, s94, s5
	s_add_i32 m0, s71, 0xc000
	ds_read_b128 v[186:189], v217
	ds_read_b128 v[190:193], v217 offset:1024
	ds_read_b128 v[194:197], v217 offset:2048
	ds_read_b128 v[198:201], v217 offset:3072
	ds_read_b128 v[202:205], v217 offset:4096
	ds_read_b128 v[206:209], v217 offset:5120
	ds_read_b128 v[218:221], v217 offset:6144
	ds_read_b128 v[222:225], v217 offset:7168
	global_load_lds_dwordx4 v178, s[0:1]
	s_add_i32 m0, s71, 0xe000
	s_nop 0
	global_load_lds_dwordx4 v180, s[0:1]
	s_waitcnt vmcnt(8)
	s_waitcnt lgkmcnt(0)
	s_barrier
	s_setprio 1
	v_mfma_f32_16x16x32_bf16 v[114:117], v[130:133], v[186:189], v[114:117]
	v_mfma_f32_16x16x32_bf16 v[126:129], v[138:141], v[186:189], v[126:129]
	v_mfma_f32_16x16x32_bf16 v[110:113], v[130:133], v[194:197], v[110:113]
	v_mfma_f32_16x16x32_bf16 v[102:105], v[138:141], v[194:197], v[102:105]
	v_mfma_f32_16x16x32_bf16 v[94:97], v[130:133], v[202:205], v[94:97]
	v_mfma_f32_16x16x32_bf16 v[86:89], v[138:141], v[202:205], v[86:89]
	v_mfma_f32_16x16x32_bf16 v[78:81], v[130:133], v[218:221], v[78:81]
	v_mfma_f32_16x16x32_bf16 v[70:73], v[138:141], v[218:221], v[70:73]
	v_mfma_f32_16x16x32_bf16 v[114:117], v[134:137], v[190:193], v[114:117]
	v_mfma_f32_16x16x32_bf16 v[126:129], v[142:145], v[190:193], v[126:129]
	v_mfma_f32_16x16x32_bf16 v[110:113], v[134:137], v[198:201], v[110:113]
	v_mfma_f32_16x16x32_bf16 v[102:105], v[142:145], v[198:201], v[102:105]
	v_mfma_f32_16x16x32_bf16 v[94:97], v[134:137], v[206:209], v[94:97]
	v_mfma_f32_16x16x32_bf16 v[86:89], v[142:145], v[206:209], v[86:89]
	v_mfma_f32_16x16x32_bf16 v[78:81], v[134:137], v[222:225], v[78:81]
	v_mfma_f32_16x16x32_bf16 v[70:73], v[142:145], v[222:225], v[70:73]
	v_mfma_f32_16x16x32_bf16 v[122:125], v[146:149], v[186:189], v[122:125]
	v_mfma_f32_16x16x32_bf16 v[118:121], v[154:157], v[186:189], v[118:121]
	v_mfma_f32_16x16x32_bf16 v[106:109], v[146:149], v[194:197], v[106:109]
	v_mfma_f32_16x16x32_bf16 v[98:101], v[154:157], v[194:197], v[98:101]
	v_mfma_f32_16x16x32_bf16 v[90:93], v[146:149], v[202:205], v[90:93]
	v_mfma_f32_16x16x32_bf16 v[82:85], v[154:157], v[202:205], v[82:85]
	v_mfma_f32_16x16x32_bf16 v[74:77], v[146:149], v[218:221], v[74:77]
	v_mfma_f32_16x16x32_bf16 v[66:69], v[154:157], v[218:221], v[66:69]
	v_mfma_f32_16x16x32_bf16 v[122:125], v[150:153], v[190:193], v[122:125]
	v_mfma_f32_16x16x32_bf16 v[118:121], v[182:185], v[190:193], v[118:121]
	v_mfma_f32_16x16x32_bf16 v[106:109], v[150:153], v[198:201], v[106:109]
	v_mfma_f32_16x16x32_bf16 v[98:101], v[182:185], v[198:201], v[98:101]
	v_mfma_f32_16x16x32_bf16 v[90:93], v[150:153], v[206:209], v[90:93]
	v_mfma_f32_16x16x32_bf16 v[82:85], v[182:185], v[206:209], v[82:85]
	v_mfma_f32_16x16x32_bf16 v[74:77], v[150:153], v[222:225], v[74:77]
	v_mfma_f32_16x16x32_bf16 v[66:69], v[182:185], v[222:225], v[66:69]
	s_setprio 0
	s_barrier
	s_add_i32 s17, s39, s70
	s_mov_b32 m0, s17
	ds_read_b128 v[186:189], v217 offset:16384
	ds_read_b128 v[190:193], v217 offset:17408
	ds_read_b128 v[194:197], v217 offset:18432
	ds_read_b128 v[198:201], v217 offset:19456
	ds_read_b128 v[202:205], v217 offset:20480
	ds_read_b128 v[206:209], v217 offset:21504
	ds_read_b128 v[218:221], v217 offset:22528
	ds_read_b128 v[222:225], v217 offset:23552
	global_load_lds_dwordx4 v160, s[40:41]
	s_add_i32 m0, s17, 0x2000
	s_add_i32 s17, s24, s70
	global_load_lds_dwordx4 v164, s[40:41]
	s_add_u32 s40, s40, s52
	s_addc_u32 s41, s41, s53
	s_mov_b32 m0, s17
	s_nop 0
	global_load_lds_dwordx4 v160, s[40:41]
	s_add_i32 m0, s17, 0x2000
	s_nop 0
	global_load_lds_dwordx4 v164, s[40:41]
	s_mov_b32 m0, s71
	s_nop 0
	global_load_lds_dwordx4 v158, s[2:3]
	s_mov_b32 m0, s34
	s_nop 0
	global_load_lds_dwordx4 v162, s[2:3]
	s_waitcnt vmcnt(8)
	s_waitcnt lgkmcnt(0)
	s_barrier
	s_setprio 1
	v_mfma_f32_16x16x32_bf16 v[62:65], v[130:133], v[186:189], v[62:65]
	v_mfma_f32_16x16x32_bf16 v[54:57], v[138:141], v[186:189], v[54:57]
	v_mfma_f32_16x16x32_bf16 v[46:49], v[130:133], v[194:197], v[46:49]
	v_mfma_f32_16x16x32_bf16 v[38:41], v[138:141], v[194:197], v[38:41]
	v_mfma_f32_16x16x32_bf16 v[30:33], v[130:133], v[202:205], v[30:33]
	v_mfma_f32_16x16x32_bf16 v[22:25], v[138:141], v[202:205], v[22:25]
	v_mfma_f32_16x16x32_bf16 v[14:17], v[130:133], v[218:221], v[14:17]
	v_mfma_f32_16x16x32_bf16 v[6:9], v[138:141], v[218:221], v[6:9]
	v_mfma_f32_16x16x32_bf16 v[62:65], v[134:137], v[190:193], v[62:65]
	v_mfma_f32_16x16x32_bf16 v[54:57], v[142:145], v[190:193], v[54:57]
	v_mfma_f32_16x16x32_bf16 v[46:49], v[134:137], v[198:201], v[46:49]
	v_mfma_f32_16x16x32_bf16 v[38:41], v[142:145], v[198:201], v[38:41]
	v_mfma_f32_16x16x32_bf16 v[30:33], v[134:137], v[206:209], v[30:33]
	v_mfma_f32_16x16x32_bf16 v[22:25], v[142:145], v[206:209], v[22:25]
	v_mfma_f32_16x16x32_bf16 v[14:17], v[134:137], v[222:225], v[14:17]
	v_mfma_f32_16x16x32_bf16 v[6:9], v[142:145], v[222:225], v[6:9]
	v_mfma_f32_16x16x32_bf16 v[58:61], v[146:149], v[186:189], v[58:61]
	v_mfma_f32_16x16x32_bf16 v[50:53], v[154:157], v[186:189], v[50:53]
	v_mfma_f32_16x16x32_bf16 v[42:45], v[146:149], v[194:197], v[42:45]
	v_mfma_f32_16x16x32_bf16 v[34:37], v[154:157], v[194:197], v[34:37]
	v_mfma_f32_16x16x32_bf16 v[26:29], v[146:149], v[202:205], v[26:29]
	v_mfma_f32_16x16x32_bf16 v[18:21], v[154:157], v[202:205], v[18:21]
	v_mfma_f32_16x16x32_bf16 v[10:13], v[146:149], v[218:221], v[10:13]
	v_mfma_f32_16x16x32_bf16 v[2:5], v[154:157], v[218:221], v[2:5]
	v_mfma_f32_16x16x32_bf16 v[58:61], v[150:153], v[190:193], v[58:61]
	v_mfma_f32_16x16x32_bf16 v[50:53], v[182:185], v[190:193], v[50:53]
	v_mfma_f32_16x16x32_bf16 v[42:45], v[150:153], v[198:201], v[42:45]
	v_mfma_f32_16x16x32_bf16 v[34:37], v[182:185], v[198:201], v[34:37]
	v_mfma_f32_16x16x32_bf16 v[26:29], v[150:153], v[206:209], v[26:29]
	v_mfma_f32_16x16x32_bf16 v[18:21], v[182:185], v[206:209], v[18:21]
	v_mfma_f32_16x16x32_bf16 v[10:13], v[150:153], v[222:225], v[10:13]
	v_mfma_f32_16x16x32_bf16 v[2:5], v[182:185], v[222:225], v[2:5]
	s_setprio 0
	s_barrier
; #define PG8_STAGE(bufoff, gbase, voff) do { _Pragma("unroll") for (int _i = 0; _i < 2; ++_i) \
;         __builtin_amdgcn_global_load_lds((const unsigned*)((const char*)(gbase) + (voff)[_i]), (LAS unsigned*)(lds + (bufoff) + ldsw + _i * 8192), 16, 0, 0); } while (0)
; #define PG8_LDA(dst, b, h) do { _Pragma("unroll") for (int m = 0; m < 4; ++m) _Pragma("unroll") for (int k = 0; k < 2; ++k) dst[m][k] = *(const LAS bf16x8*)(lds + PG8_SA(b, h) + aoff + m * 2048 + k * 1024); } while (0)
; #define PG8_LDB(dst, b, h) do { _Pragma("unroll") for (int n = 0; n < 2; ++n) _Pragma("unroll") for (int k = 0; k < 2; ++k) dst[n][k] = *(const LAS bf16x8*)(lds + PG8_SB(b, h) + boff + n * 2048 + k * 1024); } while (0)
; #define PG8_MMA(ai, bj, At, Bt) do { __builtin_amdgcn_s_setprio(1); _Pragma("unroll") for (int m = 0; m < 4; ++m) _Pragma("unroll") for (int n = 0; n < 2; ++n) _Pragma("unroll") for (int k = 0; k < 2; ++k) \
;         acc[ai][bj][m][n] = __builtin_amdgcn_mfma_f32_16x16x32_bf16(Bt[n][k], At[m][k], acc[ai][bj][m][n], 0, 0, 0); __builtin_amdgcn_s_setprio(0); } while (0)
; #define PG8_WAIT_V(n) asm volatile("s_waitcnt vmcnt(" #n ")" ::: "memory")
; #define PG8_WAIT_L(n) asm volatile("s_waitcnt lgkmcnt(" #n ")" ::: "memory")
; #define PG8_BAR __builtin_amdgcn_s_barrier()
; #define PG8_SCHED __builtin_amdgcn_sched_barrier(0)
; __device__ __forceinline__ void gemm_phase(LAS unsigned char* lds, const Gemm g, const StaticOrder& S, const Epi& E) {
;     ...
;             PG8_LDB(B0, 1, 0); PG8_LDB(B1, 1, 1); PG8_SCHED; PG8_LDA(At, 1, 0); PG8_STAGE(PG8_SA(0, 1), a2 + hstepA, voffA);
;             PG8_WAIT_V(8); PG8_WAIT_L(0); PG8_BAR; PG8_MMA(0, 0, At, B0); PG8_MMA(0, 1, At, B1); PG8_BAR; PG8_SCHED;
;             PG8_LDA(At, 1, 1); PG8_STAGE(PG8_SB(1, 0), b3, voffB); PG8_STAGE(PG8_SB(1, 1), b3 + hstepB, voffB); PG8_STAGE(PG8_SA(1, 0), a3, voffA);
;             PG8_WAIT_V(8); PG8_WAIT_L(0); PG8_BAR; PG8_MMA(1, 0, At, B0); PG8_MMA(1, 1, At, B1); PG8_BAR; PG8_SCHED;
	ds_read_b128 v[130:133], v228
	ds_read_b128 v[134:137], v228 offset:1024
	ds_read_b128 v[138:141], v228 offset:2048
	ds_read_b128 v[142:145], v228 offset:3072
	ds_read_b128 v[146:149], v229
	ds_read_b128 v[150:153], v229 offset:1024
	ds_read_b128 v[154:157], v229 offset:2048
	ds_read_b128 v[182:185], v229 offset:3072
	s_mov_b32 m0, s92
	ds_read_b128 v[186:189], v217 offset:32768
	ds_read_b128 v[190:193], v217 offset:33792
	ds_read_b128 v[194:197], v217 offset:34816
	ds_read_b128 v[198:201], v217 offset:35840
	ds_read_b128 v[202:205], v217 offset:36864
	ds_read_b128 v[206:209], v217 offset:37888
	ds_read_b128 v[218:221], v217 offset:38912
	ds_read_b128 v[222:225], v217 offset:39936
	global_load_lds_dwordx4 v178, s[2:3]
	s_mov_b32 m0, s93
	s_nop 0
	global_load_lds_dwordx4 v180, s[2:3]
	s_waitcnt vmcnt(8)
	s_waitcnt lgkmcnt(0)
	s_barrier
	s_setprio 1
	v_mfma_f32_16x16x32_bf16 v[114:117], v[130:133], v[186:189], v[114:117]
	v_mfma_f32_16x16x32_bf16 v[126:129], v[138:141], v[186:189], v[126:129]
	v_mfma_f32_16x16x32_bf16 v[110:113], v[130:133], v[194:197], v[110:113]
	v_mfma_f32_16x16x32_bf16 v[102:105], v[138:141], v[194:197], v[102:105]
	v_mfma_f32_16x16x32_bf16 v[94:97], v[130:133], v[202:205], v[94:97]
	v_mfma_f32_16x16x32_bf16 v[86:89], v[138:141], v[202:205], v[86:89]
	v_mfma_f32_16x16x32_bf16 v[78:81], v[130:133], v[218:221], v[78:81]
	v_mfma_f32_16x16x32_bf16 v[70:73], v[138:141], v[218:221], v[70:73]
	v_mfma_f32_16x16x32_bf16 v[114:117], v[134:137], v[190:193], v[114:117]
	v_mfma_f32_16x16x32_bf16 v[126:129], v[142:145], v[190:193], v[126:129]
	v_mfma_f32_16x16x32_bf16 v[110:113], v[134:137], v[198:201], v[110:113]
	v_mfma_f32_16x16x32_bf16 v[102:105], v[142:145], v[198:201], v[102:105]
	v_mfma_f32_16x16x32_bf16 v[94:97], v[134:137], v[206:209], v[94:97]
	v_mfma_f32_16x16x32_bf16 v[86:89], v[142:145], v[206:209], v[86:89]
	v_mfma_f32_16x16x32_bf16 v[78:81], v[134:137], v[222:225], v[78:81]
	v_mfma_f32_16x16x32_bf16 v[70:73], v[142:145], v[222:225], v[70:73]
	v_mfma_f32_16x16x32_bf16 v[122:125], v[146:149], v[186:189], v[122:125]
	v_mfma_f32_16x16x32_bf16 v[118:121], v[154:157], v[186:189], v[118:121]
	v_mfma_f32_16x16x32_bf16 v[106:109], v[146:149], v[194:197], v[106:109]
	v_mfma_f32_16x16x32_bf16 v[98:101], v[154:157], v[194:197], v[98:101]
	v_mfma_f32_16x16x32_bf16 v[90:93], v[146:149], v[202:205], v[90:93]
	v_mfma_f32_16x16x32_bf16 v[82:85], v[154:157], v[202:205], v[82:85]
	v_mfma_f32_16x16x32_bf16 v[74:77], v[146:149], v[218:221], v[74:77]
	v_mfma_f32_16x16x32_bf16 v[66:69], v[154:157], v[218:221], v[66:69]
	v_mfma_f32_16x16x32_bf16 v[122:125], v[150:153], v[190:193], v[122:125]
	v_mfma_f32_16x16x32_bf16 v[118:121], v[182:185], v[190:193], v[118:121]
	v_mfma_f32_16x16x32_bf16 v[106:109], v[150:153], v[198:201], v[106:109]
	v_mfma_f32_16x16x32_bf16 v[98:101], v[182:185], v[198:201], v[98:101]
	v_mfma_f32_16x16x32_bf16 v[90:93], v[150:153], v[206:209], v[90:93]
	v_mfma_f32_16x16x32_bf16 v[82:85], v[182:185], v[206:209], v[82:85]
	v_mfma_f32_16x16x32_bf16 v[74:77], v[150:153], v[222:225], v[74:77]
	v_mfma_f32_16x16x32_bf16 v[66:69], v[182:185], v[222:225], v[66:69]
	s_setprio 0
	s_barrier
	s_add_u32 s40, s40, 0x80
	s_addc_u32 s41, s41, 0
	s_sub_u32 s100, s40, s52
	s_subb_u32 s101, s41, s53
	s_add_u32 s2, s2, 0x80
	s_addc_u32 s3, s3, 0
	s_add_i32 vcc_lo, s25, s70
	s_mov_b32 m0, vcc_lo
	ds_read_b128 v[186:189], v217 offset:49152
	ds_read_b128 v[190:193], v217 offset:50176
	ds_read_b128 v[194:197], v217 offset:51200
	ds_read_b128 v[198:201], v217 offset:52224
	ds_read_b128 v[202:205], v217 offset:53248
	ds_read_b128 v[206:209], v217 offset:54272
	ds_read_b128 v[218:221], v217 offset:55296
	ds_read_b128 v[222:225], v217 offset:56320
	global_load_lds_dwordx4 v160, s[100:101]
	s_add_i32 m0, vcc_lo, 0x2000
	s_add_i32 vcc_lo, s26, s70
	global_load_lds_dwordx4 v164, s[100:101]
	s_mov_b32 m0, vcc_lo
	s_nop 0
	global_load_lds_dwordx4 v160, s[40:41]
	s_add_i32 m0, vcc_lo, 0x2000
	s_nop 0
	global_load_lds_dwordx4 v164, s[40:41]
	s_mov_b32 m0, s58
	s_nop 0
	global_load_lds_dwordx4 v158, s[2:3]
	s_mov_b32 m0, s59
	s_nop 0
	global_load_lds_dwordx4 v162, s[2:3]
	s_waitcnt vmcnt(8)
	s_waitcnt lgkmcnt(0)
	s_barrier
	s_setprio 1
	v_mfma_f32_16x16x32_bf16 v[62:65], v[130:133], v[186:189], v[62:65]
	v_mfma_f32_16x16x32_bf16 v[54:57], v[138:141], v[186:189], v[54:57]
	v_mfma_f32_16x16x32_bf16 v[46:49], v[130:133], v[194:197], v[46:49]
	v_mfma_f32_16x16x32_bf16 v[38:41], v[138:141], v[194:197], v[38:41]
	v_mfma_f32_16x16x32_bf16 v[30:33], v[130:133], v[202:205], v[30:33]
	v_mfma_f32_16x16x32_bf16 v[22:25], v[138:141], v[202:205], v[22:25]
	v_mfma_f32_16x16x32_bf16 v[14:17], v[130:133], v[218:221], v[14:17]
	v_mfma_f32_16x16x32_bf16 v[6:9], v[138:141], v[218:221], v[6:9]
	v_mfma_f32_16x16x32_bf16 v[62:65], v[134:137], v[190:193], v[62:65]
	v_mfma_f32_16x16x32_bf16 v[54:57], v[142:145], v[190:193], v[54:57]
	v_mfma_f32_16x16x32_bf16 v[46:49], v[134:137], v[198:201], v[46:49]
	v_mfma_f32_16x16x32_bf16 v[38:41], v[142:145], v[198:201], v[38:41]
	v_mfma_f32_16x16x32_bf16 v[30:33], v[134:137], v[206:209], v[30:33]
	v_mfma_f32_16x16x32_bf16 v[22:25], v[142:145], v[206:209], v[22:25]
	v_mfma_f32_16x16x32_bf16 v[14:17], v[134:137], v[222:225], v[14:17]
	v_mfma_f32_16x16x32_bf16 v[6:9], v[142:145], v[222:225], v[6:9]
	v_mfma_f32_16x16x32_bf16 v[58:61], v[146:149], v[186:189], v[58:61]
	v_mfma_f32_16x16x32_bf16 v[50:53], v[154:157], v[186:189], v[50:53]
	v_mfma_f32_16x16x32_bf16 v[42:45], v[146:149], v[194:197], v[42:45]
	v_mfma_f32_16x16x32_bf16 v[34:37], v[154:157], v[194:197], v[34:37]
	v_mfma_f32_16x16x32_bf16 v[26:29], v[146:149], v[202:205], v[26:29]
	v_mfma_f32_16x16x32_bf16 v[18:21], v[154:157], v[202:205], v[18:21]
	v_mfma_f32_16x16x32_bf16 v[10:13], v[146:149], v[218:221], v[10:13]
	v_mfma_f32_16x16x32_bf16 v[2:5], v[154:157], v[218:221], v[2:5]
	v_mfma_f32_16x16x32_bf16 v[58:61], v[150:153], v[190:193], v[58:61]
	v_mfma_f32_16x16x32_bf16 v[50:53], v[182:185], v[190:193], v[50:53]
	v_mfma_f32_16x16x32_bf16 v[42:45], v[150:153], v[198:201], v[42:45]
	v_mfma_f32_16x16x32_bf16 v[34:37], v[182:185], v[198:201], v[34:37]
	v_mfma_f32_16x16x32_bf16 v[26:29], v[150:153], v[206:209], v[26:29]
	v_mfma_f32_16x16x32_bf16 v[18:21], v[182:185], v[206:209], v[18:21]
	v_mfma_f32_16x16x32_bf16 v[10:13], v[150:153], v[222:225], v[10:13]
	v_mfma_f32_16x16x32_bf16 v[2:5], v[182:185], v[222:225], v[2:5]
	s_setprio 0
	s_barrier
	s_add_u32 s0, s0, 0x100
	s_addc_u32 s1, s1, 0
	s_add_u32 s5, s5, 0x100
	s_addc_u32 s16, s16, 0
	s_cmp_ge_i32 s27, s84
	s_mov_b32 s17, s27
	s_cbranch_scc0 .LBB0_177
	s_and_b64 vcc, exec, s[74:75]
	s_cbranch_vccz .LBB0_180
